# plus: accumulator clear moved into the first K-loop trip behind its LDS reads and tile loads (GU, QKV, SGU-in loops)
# speedup vs baseline: 1.0062x; 1.0036x over previous
.LBB0_71:
	s_add_u32 s0, s0, 0x40080
	s_addc_u32 s1, s1, 0
	s_add_u32 s25, s4, 0x100
	s_addc_u32 s26, s5, 0
	s_mov_b32 s27, -2
.LBB0_72:
	s_add_u32 s4, s0, 0xfffc0080
	s_addc_u32 s5, s1, -1
	s_add_i32 s30, 0, 0x10000
	s_cmp_eq_u32 s27, 12
	s_cselect_b32 s7, s59, s5
	s_cselect_b32 s6, s58, s4
	s_cselect_b32 s5, s61, s26
	s_cselect_b32 s4, s60, s25
	s_add_i32 s33, 0, 0x14000
	v_add_u32_e32 v46, s30, v169
	v_add_u32_e32 v164, s33, v169
	ds_read_b128 v[34:37], v46
	ds_read_b128 v[38:41], v46 offset:1024
	ds_read_b128 v[42:45], v46 offset:2048
	ds_read_b128 v[46:49], v46 offset:3072
	ds_read_b128 v[156:159], v164
	ds_read_b128 v[160:163], v164 offset:1024
	ds_read_b128 v[172:175], v164 offset:2048
	ds_read_b128 v[176:179], v164 offset:3072
	v_lshl_add_u64 v[166:167], s[0:1], 0, v[152:153]
	s_add_i32 m0, s13, 0xc000
	ds_read_b128 v[180:183], v170
	ds_read_b128 v[184:187], v170 offset:1024
	ds_read_b128 v[188:191], v170 offset:2048
	ds_read_b128 v[192:195], v170 offset:3072
	ds_read_b128 v[196:199], v170 offset:4096
	ds_read_b128 v[216:219], v170 offset:5120
	ds_read_b128 v[220:223], v170 offset:6144
	ds_read_b128 v[224:227], v170 offset:7168
	global_load_lds_dwordx4 v[166:167], off
	v_lshl_add_u64 v[166:167], s[0:1], 0, v[154:155]
	s_add_i32 m0, s13, 0xe000
	s_nop 0
	global_load_lds_dwordx4 v[166:167], off
	s_cmp_lg_u32 s27, -2
	s_cbranch_scc1 .Lzf1_skip
	v_mov_b64_e32 v[2:3], 0
	v_mov_b64_e32 v[4:5], 0
	v_mov_b64_e32 v[6:7], 0
	v_mov_b64_e32 v[8:9], 0
	v_mov_b64_e32 v[10:11], 0
	v_mov_b64_e32 v[12:13], 0
	v_mov_b64_e32 v[14:15], 0
	v_mov_b64_e32 v[16:17], 0
	v_mov_b64_e32 v[18:19], 0
	v_mov_b64_e32 v[20:21], 0
	v_mov_b64_e32 v[22:23], 0
	v_mov_b64_e32 v[24:25], 0
	v_mov_b64_e32 v[26:27], 0
	v_mov_b64_e32 v[28:29], 0
	v_mov_b64_e32 v[30:31], 0
	v_mov_b64_e32 v[32:33], 0
	v_mov_b64_e32 v[50:51], 0
	v_mov_b64_e32 v[52:53], 0
	v_mov_b64_e32 v[54:55], 0
	v_mov_b64_e32 v[56:57], 0
	v_mov_b64_e32 v[58:59], 0
	v_mov_b64_e32 v[60:61], 0
	v_mov_b64_e32 v[62:63], 0
	v_mov_b64_e32 v[64:65], 0
	v_mov_b64_e32 v[66:67], 0
	v_mov_b64_e32 v[68:69], 0
	v_mov_b64_e32 v[70:71], 0
	v_mov_b64_e32 v[72:73], 0
	v_mov_b64_e32 v[74:75], 0
	v_mov_b64_e32 v[76:77], 0
	v_mov_b64_e32 v[78:79], 0
	v_mov_b64_e32 v[80:81], 0
	v_mov_b64_e32 v[82:83], 0
	v_mov_b64_e32 v[84:85], 0
	v_mov_b64_e32 v[86:87], 0
	v_mov_b64_e32 v[88:89], 0
	v_mov_b64_e32 v[90:91], 0
	v_mov_b64_e32 v[92:93], 0
	v_mov_b64_e32 v[94:95], 0
	v_mov_b64_e32 v[96:97], 0
	v_mov_b64_e32 v[98:99], 0
	v_mov_b64_e32 v[100:101], 0
	v_mov_b64_e32 v[102:103], 0
	v_mov_b64_e32 v[104:105], 0
	v_mov_b64_e32 v[106:107], 0
	v_mov_b64_e32 v[108:109], 0
	v_mov_b64_e32 v[110:111], 0
	v_mov_b64_e32 v[112:113], 0
	v_mov_b64_e32 v[114:115], 0
	v_mov_b64_e32 v[116:117], 0
	v_mov_b64_e32 v[118:119], 0
	v_mov_b64_e32 v[120:121], 0
	v_mov_b64_e32 v[122:123], 0
	v_mov_b64_e32 v[124:125], 0
	v_mov_b64_e32 v[126:127], 0
	v_mov_b64_e32 v[128:129], 0
	v_mov_b64_e32 v[130:131], 0
	v_mov_b64_e32 v[132:133], 0
	v_mov_b64_e32 v[134:135], 0
	v_mov_b64_e32 v[136:137], 0
	v_mov_b64_e32 v[138:139], 0
	v_mov_b64_e32 v[140:141], 0
	v_mov_b64_e32 v[142:143], 0
	v_mov_b64_e32 v[144:145], 0
.Lzf1_skip:
	s_waitcnt vmcnt(8)
	s_waitcnt lgkmcnt(0)
	s_barrier
	s_setprio 1
	s_waitcnt lgkmcnt(0)
	v_mfma_f32_16x16x32_bf16 v[142:145], v[34:37], v[180:183], v[142:145]
	v_mfma_f32_16x16x32_bf16 v[138:141], v[42:45], v[180:183], v[138:141]
	v_mfma_f32_16x16x32_bf16 v[126:129], v[34:37], v[188:191], v[126:129]
	v_mfma_f32_16x16x32_bf16 v[122:125], v[42:45], v[188:191], v[122:125]
	v_mfma_f32_16x16x32_bf16 v[110:113], v[34:37], v[196:199], v[110:113]
	v_mfma_f32_16x16x32_bf16 v[106:109], v[42:45], v[196:199], v[106:109]
	v_mfma_f32_16x16x32_bf16 v[94:97], v[34:37], v[220:223], v[94:97]
	v_mfma_f32_16x16x32_bf16 v[90:93], v[42:45], v[220:223], v[90:93]
	v_mfma_f32_16x16x32_bf16 v[142:145], v[38:41], v[184:187], v[142:145]
	v_mfma_f32_16x16x32_bf16 v[138:141], v[46:49], v[184:187], v[138:141]
	v_mfma_f32_16x16x32_bf16 v[126:129], v[38:41], v[192:195], v[126:129]
	v_mfma_f32_16x16x32_bf16 v[122:125], v[46:49], v[192:195], v[122:125]
	v_mfma_f32_16x16x32_bf16 v[110:113], v[38:41], v[216:219], v[110:113]
	v_mfma_f32_16x16x32_bf16 v[106:109], v[46:49], v[216:219], v[106:109]
	v_mfma_f32_16x16x32_bf16 v[94:97], v[38:41], v[224:227], v[94:97]
	v_mfma_f32_16x16x32_bf16 v[90:93], v[46:49], v[224:227], v[90:93]
	s_setprio 0
	s_setprio 1
	v_mfma_f32_16x16x32_bf16 v[134:137], v[156:159], v[180:183], v[134:137]
	v_mfma_f32_16x16x32_bf16 v[130:133], v[172:175], v[180:183], v[130:133]
	v_mfma_f32_16x16x32_bf16 v[118:121], v[156:159], v[188:191], v[118:121]
	v_mfma_f32_16x16x32_bf16 v[114:117], v[172:175], v[188:191], v[114:117]
	v_mfma_f32_16x16x32_bf16 v[102:105], v[156:159], v[196:199], v[102:105]
	v_mfma_f32_16x16x32_bf16 v[98:101], v[172:175], v[196:199], v[98:101]
	v_mfma_f32_16x16x32_bf16 v[86:89], v[156:159], v[220:223], v[86:89]
	v_mfma_f32_16x16x32_bf16 v[82:85], v[172:175], v[220:223], v[82:85]
	v_mfma_f32_16x16x32_bf16 v[134:137], v[160:163], v[184:187], v[134:137]
	v_mfma_f32_16x16x32_bf16 v[130:133], v[176:179], v[184:187], v[130:133]
	v_mfma_f32_16x16x32_bf16 v[118:121], v[160:163], v[192:195], v[118:121]
	v_mfma_f32_16x16x32_bf16 v[114:117], v[176:179], v[192:195], v[114:117]
	v_mfma_f32_16x16x32_bf16 v[102:105], v[160:163], v[216:219], v[102:105]
	v_mfma_f32_16x16x32_bf16 v[98:101], v[176:179], v[216:219], v[98:101]
	v_mfma_f32_16x16x32_bf16 v[86:89], v[160:163], v[224:227], v[86:89]
	v_mfma_f32_16x16x32_bf16 v[82:85], v[176:179], v[224:227], v[82:85]
	s_setprio 0
	s_barrier
	s_add_i32 s30, s30, s12
	v_lshl_add_u64 v[166:167], s[4:5], 0, v[0:1]
	s_mov_b32 m0, s30
	ds_read_b128 v[180:183], v170 offset:16384
	ds_read_b128 v[184:187], v170 offset:17408
	ds_read_b128 v[188:191], v170 offset:18432
	ds_read_b128 v[192:195], v170 offset:19456
	ds_read_b128 v[196:199], v170 offset:20480
	ds_read_b128 v[216:219], v170 offset:21504
	ds_read_b128 v[220:223], v170 offset:22528
	ds_read_b128 v[224:227], v170 offset:23552
	global_load_lds_dwordx4 v[166:167], off
	s_add_i32 m0, s30, 0x2000
	s_add_u32 s36, s4, 0x40000
	v_lshl_add_u64 v[200:201], s[4:5], 0, v[150:151]
	s_addc_u32 s37, s5, 0
	s_add_i32 s30, s33, s12
	global_load_lds_dwordx4 v[200:201], off
	v_lshl_add_u64 v[208:209], s[36:37], 0, v[0:1]
	s_mov_b32 m0, s30
	v_lshl_add_u64 v[228:229], s[6:7], 0, v[148:149]
	global_load_lds_dwordx4 v[208:209], off
	v_lshl_add_u64 v[208:209], s[36:37], 0, v[150:151]
	s_add_i32 m0, s30, 0x2000
	s_nop 0
	global_load_lds_dwordx4 v[208:209], off
	v_lshl_add_u64 v[208:209], s[6:7], 0, v[146:147]
	s_mov_b32 m0, s13
	s_nop 0
	global_load_lds_dwordx4 v[208:209], off
	s_mov_b32 m0, s14
	s_nop 0
	global_load_lds_dwordx4 v[228:229], off
	s_waitcnt vmcnt(8)
	s_waitcnt lgkmcnt(0)
	s_barrier
	s_setprio 1
	s_waitcnt lgkmcnt(0)
	v_mfma_f32_16x16x32_bf16 v[78:81], v[34:37], v[180:183], v[78:81]
	v_mfma_f32_16x16x32_bf16 v[74:77], v[42:45], v[180:183], v[74:77]
	v_mfma_f32_16x16x32_bf16 v[62:65], v[34:37], v[188:191], v[62:65]
	v_mfma_f32_16x16x32_bf16 v[58:61], v[42:45], v[188:191], v[58:61]
	v_mfma_f32_16x16x32_bf16 v[30:33], v[34:37], v[196:199], v[30:33]
	v_mfma_f32_16x16x32_bf16 v[26:29], v[42:45], v[196:199], v[26:29]
	v_mfma_f32_16x16x32_bf16 v[14:17], v[34:37], v[220:223], v[14:17]
	v_mfma_f32_16x16x32_bf16 v[10:13], v[42:45], v[220:223], v[10:13]
	v_mfma_f32_16x16x32_bf16 v[78:81], v[38:41], v[184:187], v[78:81]
	v_mfma_f32_16x16x32_bf16 v[74:77], v[46:49], v[184:187], v[74:77]
	v_mfma_f32_16x16x32_bf16 v[62:65], v[38:41], v[192:195], v[62:65]
	v_mfma_f32_16x16x32_bf16 v[58:61], v[46:49], v[192:195], v[58:61]
	v_mfma_f32_16x16x32_bf16 v[30:33], v[38:41], v[216:219], v[30:33]
	v_mfma_f32_16x16x32_bf16 v[26:29], v[46:49], v[216:219], v[26:29]
	v_mfma_f32_16x16x32_bf16 v[14:17], v[38:41], v[224:227], v[14:17]
	v_mfma_f32_16x16x32_bf16 v[10:13], v[46:49], v[224:227], v[10:13]
	s_setprio 0
	s_setprio 1
	v_mfma_f32_16x16x32_bf16 v[22:25], v[156:159], v[196:199], v[22:25]
	v_mfma_f32_16x16x32_bf16 v[18:21], v[172:175], v[196:199], v[18:21]
	v_mfma_f32_16x16x32_bf16 v[6:9], v[156:159], v[220:223], v[6:9]
	v_mfma_f32_16x16x32_bf16 v[2:5], v[172:175], v[220:223], v[2:5]
	v_mfma_f32_16x16x32_bf16 v[34:37], v[156:159], v[180:183], v[70:73]
	v_mfma_f32_16x16x32_bf16 v[38:41], v[172:175], v[180:183], v[66:69]
	v_mfma_f32_16x16x32_bf16 v[42:45], v[156:159], v[188:191], v[54:57]
	v_mfma_f32_16x16x32_bf16 v[46:49], v[172:175], v[188:191], v[50:53]
	v_mfma_f32_16x16x32_bf16 v[22:25], v[160:163], v[216:219], v[22:25]
	v_mfma_f32_16x16x32_bf16 v[18:21], v[176:179], v[216:219], v[18:21]
	v_mfma_f32_16x16x32_bf16 v[6:9], v[160:163], v[224:227], v[6:9]
	v_mfma_f32_16x16x32_bf16 v[2:5], v[176:179], v[224:227], v[2:5]
	v_mfma_f32_16x16x32_bf16 v[34:37], v[160:163], v[184:187], v[34:37]
	v_mfma_f32_16x16x32_bf16 v[38:41], v[176:179], v[184:187], v[38:41]
	v_mfma_f32_16x16x32_bf16 v[42:45], v[160:163], v[192:195], v[42:45]
	v_mfma_f32_16x16x32_bf16 v[46:49], v[176:179], v[192:195], v[46:49]
	s_setprio 0
	s_barrier
	s_add_i32 s30, 0, 0x18000
	s_add_i32 s33, 0, 0x1c000
	v_add_u32_e32 v70, s30, v169
	v_add_u32_e32 v164, s33, v169
	ds_read_b128 v[50:53], v70
	ds_read_b128 v[54:57], v70 offset:1024
	ds_read_b128 v[66:69], v70 offset:2048
	ds_read_b128 v[70:73], v70 offset:3072
	ds_read_b128 v[156:159], v164
	ds_read_b128 v[160:163], v164 offset:1024
	ds_read_b128 v[172:175], v164 offset:2048
	ds_read_b128 v[176:179], v164 offset:3072
	s_add_u32 s6, s6, 0x40000
	s_addc_u32 s7, s7, 0
	s_mov_b32 m0, s15
	v_lshl_add_u64 v[230:231], s[6:7], 0, v[146:147]
	ds_read_b128 v[180:183], v170 offset:32768
	ds_read_b128 v[184:187], v170 offset:33792
	ds_read_b128 v[188:191], v170 offset:34816
	ds_read_b128 v[192:195], v170 offset:35840
	ds_read_b128 v[196:199], v170 offset:36864
	ds_read_b128 v[216:219], v170 offset:37888
	ds_read_b128 v[220:223], v170 offset:38912
	ds_read_b128 v[224:227], v170 offset:39936
	global_load_lds_dwordx4 v[230:231], off
	v_lshl_add_u64 v[230:231], s[6:7], 0, v[148:149]
	s_mov_b32 m0, s16
	s_nop 0
	global_load_lds_dwordx4 v[230:231], off
	s_waitcnt vmcnt(8)
	s_waitcnt lgkmcnt(0)
	s_barrier
	s_setprio 1
	s_waitcnt lgkmcnt(0)
	v_mfma_f32_16x16x32_bf16 v[142:145], v[50:53], v[180:183], v[142:145]
	v_mfma_f32_16x16x32_bf16 v[138:141], v[66:69], v[180:183], v[138:141]
	v_mfma_f32_16x16x32_bf16 v[126:129], v[50:53], v[188:191], v[126:129]
	v_mfma_f32_16x16x32_bf16 v[122:125], v[66:69], v[188:191], v[122:125]
	v_mfma_f32_16x16x32_bf16 v[110:113], v[50:53], v[196:199], v[110:113]
	v_mfma_f32_16x16x32_bf16 v[106:109], v[66:69], v[196:199], v[106:109]
	v_mfma_f32_16x16x32_bf16 v[94:97], v[50:53], v[220:223], v[94:97]
	v_mfma_f32_16x16x32_bf16 v[90:93], v[66:69], v[220:223], v[90:93]
	v_mfma_f32_16x16x32_bf16 v[142:145], v[54:57], v[184:187], v[142:145]
	v_mfma_f32_16x16x32_bf16 v[138:141], v[70:73], v[184:187], v[138:141]
	v_mfma_f32_16x16x32_bf16 v[126:129], v[54:57], v[192:195], v[126:129]
	v_mfma_f32_16x16x32_bf16 v[122:125], v[70:73], v[192:195], v[122:125]
	v_mfma_f32_16x16x32_bf16 v[110:113], v[54:57], v[216:219], v[110:113]
	v_mfma_f32_16x16x32_bf16 v[106:109], v[70:73], v[216:219], v[106:109]
	v_mfma_f32_16x16x32_bf16 v[94:97], v[54:57], v[224:227], v[94:97]
	v_mfma_f32_16x16x32_bf16 v[90:93], v[70:73], v[224:227], v[90:93]
	s_setprio 0
	s_setprio 1
	v_mfma_f32_16x16x32_bf16 v[134:137], v[156:159], v[180:183], v[134:137]
	v_mfma_f32_16x16x32_bf16 v[130:133], v[172:175], v[180:183], v[130:133]
	v_mfma_f32_16x16x32_bf16 v[118:121], v[156:159], v[188:191], v[118:121]
	v_mfma_f32_16x16x32_bf16 v[114:117], v[172:175], v[188:191], v[114:117]
	v_mfma_f32_16x16x32_bf16 v[102:105], v[156:159], v[196:199], v[102:105]
	v_mfma_f32_16x16x32_bf16 v[98:101], v[172:175], v[196:199], v[98:101]
	v_mfma_f32_16x16x32_bf16 v[86:89], v[156:159], v[220:223], v[86:89]
	v_mfma_f32_16x16x32_bf16 v[82:85], v[172:175], v[220:223], v[82:85]
	v_mfma_f32_16x16x32_bf16 v[134:137], v[160:163], v[184:187], v[134:137]
	v_mfma_f32_16x16x32_bf16 v[130:133], v[176:179], v[184:187], v[130:133]
	v_mfma_f32_16x16x32_bf16 v[118:121], v[160:163], v[192:195], v[118:121]
	v_mfma_f32_16x16x32_bf16 v[114:117], v[176:179], v[192:195], v[114:117]
	v_mfma_f32_16x16x32_bf16 v[102:105], v[160:163], v[216:219], v[102:105]
	v_mfma_f32_16x16x32_bf16 v[98:101], v[176:179], v[216:219], v[98:101]
	v_mfma_f32_16x16x32_bf16 v[86:89], v[160:163], v[224:227], v[86:89]
	v_mfma_f32_16x16x32_bf16 v[82:85], v[176:179], v[224:227], v[82:85]
	s_setprio 0
	s_barrier
	s_add_i32 s6, s30, s12
	v_lshl_add_u64 v[166:167], v[166:167], 0, s[96:97]
	s_mov_b32 m0, s6
	ds_read_b128 v[180:183], v170 offset:49152
	ds_read_b128 v[184:187], v170 offset:50176
	ds_read_b128 v[188:191], v170 offset:51200
	ds_read_b128 v[192:195], v170 offset:52224
	ds_read_b128 v[196:199], v170 offset:53248
	ds_read_b128 v[216:219], v170 offset:54272
	ds_read_b128 v[220:223], v170 offset:55296
	ds_read_b128 v[224:227], v170 offset:56320
	global_load_lds_dwordx4 v[166:167], off
	s_add_i32 m0, s6, 0x2000
	s_add_u32 s4, s4, 0x40080
	v_lshl_add_u64 v[166:167], v[200:201], 0, s[96:97]
	s_addc_u32 s5, s5, 0
	s_add_i32 s6, s33, s12
	global_load_lds_dwordx4 v[166:167], off
	v_lshl_add_u64 v[166:167], s[4:5], 0, v[0:1]
	s_mov_b32 m0, s6
	s_nop 0
	global_load_lds_dwordx4 v[166:167], off
	v_lshl_add_u64 v[166:167], s[4:5], 0, v[150:151]
	s_add_i32 m0, s6, 0x2000
	s_nop 0
	global_load_lds_dwordx4 v[166:167], off
	v_lshl_add_u64 v[166:167], v[208:209], 0, s[96:97]
	s_mov_b32 m0, s19
	s_nop 0
	global_load_lds_dwordx4 v[166:167], off
	v_lshl_add_u64 v[166:167], v[228:229], 0, s[96:97]
	s_mov_b32 m0, s20
	s_nop 0
	global_load_lds_dwordx4 v[166:167], off
	s_waitcnt vmcnt(8)
	s_waitcnt lgkmcnt(0)
	s_barrier
	s_setprio 1
	s_waitcnt lgkmcnt(0)
	v_mfma_f32_16x16x32_bf16 v[78:81], v[50:53], v[180:183], v[78:81]
	v_mfma_f32_16x16x32_bf16 v[74:77], v[66:69], v[180:183], v[74:77]
	v_mfma_f32_16x16x32_bf16 v[62:65], v[50:53], v[188:191], v[62:65]
	v_mfma_f32_16x16x32_bf16 v[58:61], v[66:69], v[188:191], v[58:61]
	v_mfma_f32_16x16x32_bf16 v[30:33], v[50:53], v[196:199], v[30:33]
	v_mfma_f32_16x16x32_bf16 v[26:29], v[66:69], v[196:199], v[26:29]
	v_mfma_f32_16x16x32_bf16 v[14:17], v[50:53], v[220:223], v[14:17]
	v_mfma_f32_16x16x32_bf16 v[10:13], v[66:69], v[220:223], v[10:13]
	v_mfma_f32_16x16x32_bf16 v[78:81], v[54:57], v[184:187], v[78:81]
	v_mfma_f32_16x16x32_bf16 v[74:77], v[70:73], v[184:187], v[74:77]
	v_mfma_f32_16x16x32_bf16 v[62:65], v[54:57], v[192:195], v[62:65]
	v_mfma_f32_16x16x32_bf16 v[58:61], v[70:73], v[192:195], v[58:61]
	v_mfma_f32_16x16x32_bf16 v[30:33], v[54:57], v[216:219], v[30:33]
	v_mfma_f32_16x16x32_bf16 v[26:29], v[70:73], v[216:219], v[26:29]
	v_mfma_f32_16x16x32_bf16 v[14:17], v[54:57], v[224:227], v[14:17]
	v_mfma_f32_16x16x32_bf16 v[10:13], v[70:73], v[224:227], v[10:13]
	s_setprio 0
	s_setprio 1
	v_mfma_f32_16x16x32_bf16 v[34:37], v[156:159], v[180:183], v[34:37]
	v_mfma_f32_16x16x32_bf16 v[70:73], v[160:163], v[184:187], v[34:37]
	v_mfma_f32_16x16x32_bf16 v[34:37], v[172:175], v[180:183], v[38:41]
	v_mfma_f32_16x16x32_bf16 v[66:69], v[176:179], v[184:187], v[34:37]
	v_mfma_f32_16x16x32_bf16 v[34:37], v[156:159], v[188:191], v[42:45]
	v_mfma_f32_16x16x32_bf16 v[54:57], v[160:163], v[192:195], v[34:37]
	v_mfma_f32_16x16x32_bf16 v[34:37], v[172:175], v[188:191], v[46:49]
	v_mfma_f32_16x16x32_bf16 v[22:25], v[156:159], v[196:199], v[22:25]
	v_mfma_f32_16x16x32_bf16 v[18:21], v[172:175], v[196:199], v[18:21]
	v_mfma_f32_16x16x32_bf16 v[6:9], v[156:159], v[220:223], v[6:9]
	v_mfma_f32_16x16x32_bf16 v[2:5], v[172:175], v[220:223], v[2:5]
	v_mfma_f32_16x16x32_bf16 v[50:53], v[176:179], v[192:195], v[34:37]
	v_mfma_f32_16x16x32_bf16 v[22:25], v[160:163], v[216:219], v[22:25]
	v_mfma_f32_16x16x32_bf16 v[18:21], v[176:179], v[216:219], v[18:21]
	v_mfma_f32_16x16x32_bf16 v[6:9], v[160:163], v[224:227], v[6:9]
	v_mfma_f32_16x16x32_bf16 v[2:5], v[176:179], v[224:227], v[2:5]
	s_setprio 0
	s_barrier
	s_add_i32 s27, s27, 2
	s_add_u32 s0, s0, 0x100
	s_addc_u32 s1, s1, 0
	s_add_u32 s25, s25, 0x100
	s_addc_u32 s26, s26, 0
	s_cmp_gt_u32 s27, 13
	s_cbranch_scc0 .LBB0_72
	s_and_b64 vcc, exec, s[50:51]
	s_cbranch_vccz .LBB0_75
	s_barrier

.LBB0_146:
	s_add_u32 s0, s0, 0x40080
	s_addc_u32 s1, s1, 0
	s_add_u32 s2, s4, 0x100
	s_addc_u32 s3, s5, 0
	s_mov_b32 s8, -2
.LBB0_147:
	s_add_u32 s4, s0, 0xfffc0080
	s_addc_u32 s5, s1, -1
	s_add_i32 s9, 0, 0x10000
	s_cmp_eq_u32 s8, 12
	s_cselect_b32 s7, s59, s5
	s_cselect_b32 s6, s58, s4
	s_cselect_b32 s5, s61, s3
	s_cselect_b32 s4, s60, s2
	s_add_i32 s13, 0, 0x14000
	v_add_u32_e32 v142, s9, v200
	v_add_u32_e32 v158, s13, v200
	ds_read_b128 v[130:133], v142
	ds_read_b128 v[134:137], v142 offset:1024
	ds_read_b128 v[138:141], v142 offset:2048
	ds_read_b128 v[142:145], v142 offset:3072
	ds_read_b128 v[146:149], v158
	ds_read_b128 v[150:153], v158 offset:1024
	ds_read_b128 v[154:157], v158 offset:2048
	ds_read_b128 v[158:161], v158 offset:3072
	v_lshl_add_u64 v[208:209], s[0:1], 0, v[166:167]
	s_add_i32 m0, s19, 0xc000
	ds_read_b128 v[170:173], v201
	ds_read_b128 v[174:177], v201 offset:1024
	ds_read_b128 v[178:181], v201 offset:2048
	ds_read_b128 v[182:185], v201 offset:3072
	ds_read_b128 v[186:189], v201 offset:4096
	ds_read_b128 v[190:193], v201 offset:5120
	ds_read_b128 v[194:197], v201 offset:6144
	ds_read_b128 v[216:219], v201 offset:7168
	global_load_lds_dwordx4 v[208:209], off
	v_lshl_add_u64 v[208:209], s[0:1], 0, v[168:169]
	s_add_i32 m0, s19, 0xe000
	s_nop 0
	global_load_lds_dwordx4 v[208:209], off
	s_cmp_lg_u32 s8, -2
	s_cbranch_scc1 .Lzf2_skip
	v_mov_b64_e32 v[2:3], 0
	v_mov_b64_e32 v[4:5], 0
	v_mov_b64_e32 v[6:7], 0
	v_mov_b64_e32 v[8:9], 0
	v_mov_b64_e32 v[10:11], 0
	v_mov_b64_e32 v[12:13], 0
	v_mov_b64_e32 v[14:15], 0
	v_mov_b64_e32 v[16:17], 0
	v_mov_b64_e32 v[18:19], 0
	v_mov_b64_e32 v[20:21], 0
	v_mov_b64_e32 v[22:23], 0
	v_mov_b64_e32 v[24:25], 0
	v_mov_b64_e32 v[26:27], 0
	v_mov_b64_e32 v[28:29], 0
	v_mov_b64_e32 v[30:31], 0
	v_mov_b64_e32 v[32:33], 0
	v_mov_b64_e32 v[34:35], 0
	v_mov_b64_e32 v[36:37], 0
	v_mov_b64_e32 v[38:39], 0
	v_mov_b64_e32 v[40:41], 0
	v_mov_b64_e32 v[42:43], 0
	v_mov_b64_e32 v[44:45], 0
	v_mov_b64_e32 v[46:47], 0
	v_mov_b64_e32 v[48:49], 0
	v_mov_b64_e32 v[50:51], 0
	v_mov_b64_e32 v[52:53], 0
	v_mov_b64_e32 v[54:55], 0
	v_mov_b64_e32 v[56:57], 0
	v_mov_b64_e32 v[58:59], 0
	v_mov_b64_e32 v[60:61], 0
	v_mov_b64_e32 v[62:63], 0
	v_mov_b64_e32 v[64:65], 0
	v_mov_b64_e32 v[66:67], 0
	v_mov_b64_e32 v[68:69], 0
	v_mov_b64_e32 v[70:71], 0
	v_mov_b64_e32 v[72:73], 0
	v_mov_b64_e32 v[74:75], 0
	v_mov_b64_e32 v[76:77], 0
	v_mov_b64_e32 v[78:79], 0
	v_mov_b64_e32 v[80:81], 0
	v_mov_b64_e32 v[82:83], 0
	v_mov_b64_e32 v[84:85], 0
	v_mov_b64_e32 v[86:87], 0
	v_mov_b64_e32 v[88:89], 0
	v_mov_b64_e32 v[90:91], 0
	v_mov_b64_e32 v[92:93], 0
	v_mov_b64_e32 v[94:95], 0
	v_mov_b64_e32 v[96:97], 0
	v_mov_b64_e32 v[98:99], 0
	v_mov_b64_e32 v[100:101], 0
	v_mov_b64_e32 v[102:103], 0
	v_mov_b64_e32 v[104:105], 0
	v_mov_b64_e32 v[106:107], 0
	v_mov_b64_e32 v[108:109], 0
	v_mov_b64_e32 v[110:111], 0
	v_mov_b64_e32 v[112:113], 0
	v_mov_b64_e32 v[114:115], 0
	v_mov_b64_e32 v[116:117], 0
	v_mov_b64_e32 v[118:119], 0
	v_mov_b64_e32 v[120:121], 0
	v_mov_b64_e32 v[122:123], 0
	v_mov_b64_e32 v[124:125], 0
	v_mov_b64_e32 v[126:127], 0
	v_mov_b64_e32 v[128:129], 0
.Lzf2_skip:
	s_waitcnt vmcnt(8)
	s_waitcnt lgkmcnt(0)
	s_barrier
	s_setprio 1
	s_waitcnt lgkmcnt(0)
	v_mfma_f32_16x16x32_bf16 v[126:129], v[130:133], v[170:173], v[126:129]
	v_mfma_f32_16x16x32_bf16 v[122:125], v[138:141], v[170:173], v[122:125]
	v_mfma_f32_16x16x32_bf16 v[110:113], v[130:133], v[178:181], v[110:113]
	v_mfma_f32_16x16x32_bf16 v[106:109], v[138:141], v[178:181], v[106:109]
	v_mfma_f32_16x16x32_bf16 v[94:97], v[130:133], v[186:189], v[94:97]
	v_mfma_f32_16x16x32_bf16 v[90:93], v[138:141], v[186:189], v[90:93]
	v_mfma_f32_16x16x32_bf16 v[78:81], v[130:133], v[194:197], v[78:81]
	v_mfma_f32_16x16x32_bf16 v[74:77], v[138:141], v[194:197], v[74:77]
	v_mfma_f32_16x16x32_bf16 v[126:129], v[134:137], v[174:177], v[126:129]
	v_mfma_f32_16x16x32_bf16 v[122:125], v[142:145], v[174:177], v[122:125]
	v_mfma_f32_16x16x32_bf16 v[110:113], v[134:137], v[182:185], v[110:113]
	v_mfma_f32_16x16x32_bf16 v[106:109], v[142:145], v[182:185], v[106:109]
	v_mfma_f32_16x16x32_bf16 v[94:97], v[134:137], v[190:193], v[94:97]
	v_mfma_f32_16x16x32_bf16 v[90:93], v[142:145], v[190:193], v[90:93]
	v_mfma_f32_16x16x32_bf16 v[78:81], v[134:137], v[216:219], v[78:81]
	v_mfma_f32_16x16x32_bf16 v[74:77], v[142:145], v[216:219], v[74:77]
	s_setprio 0
	s_setprio 1
	v_mfma_f32_16x16x32_bf16 v[118:121], v[146:149], v[170:173], v[118:121]
	v_mfma_f32_16x16x32_bf16 v[114:117], v[154:157], v[170:173], v[114:117]
	v_mfma_f32_16x16x32_bf16 v[102:105], v[146:149], v[178:181], v[102:105]
	v_mfma_f32_16x16x32_bf16 v[98:101], v[154:157], v[178:181], v[98:101]
	v_mfma_f32_16x16x32_bf16 v[86:89], v[146:149], v[186:189], v[86:89]
	v_mfma_f32_16x16x32_bf16 v[82:85], v[154:157], v[186:189], v[82:85]
	v_mfma_f32_16x16x32_bf16 v[70:73], v[146:149], v[194:197], v[70:73]
	v_mfma_f32_16x16x32_bf16 v[66:69], v[154:157], v[194:197], v[66:69]
	v_mfma_f32_16x16x32_bf16 v[118:121], v[150:153], v[174:177], v[118:121]
	v_mfma_f32_16x16x32_bf16 v[114:117], v[158:161], v[174:177], v[114:117]
	v_mfma_f32_16x16x32_bf16 v[102:105], v[150:153], v[182:185], v[102:105]
	v_mfma_f32_16x16x32_bf16 v[98:101], v[158:161], v[182:185], v[98:101]
	v_mfma_f32_16x16x32_bf16 v[86:89], v[150:153], v[190:193], v[86:89]
	v_mfma_f32_16x16x32_bf16 v[82:85], v[158:161], v[190:193], v[82:85]
	v_mfma_f32_16x16x32_bf16 v[70:73], v[150:153], v[216:219], v[70:73]
	v_mfma_f32_16x16x32_bf16 v[66:69], v[158:161], v[216:219], v[66:69]
	s_setprio 0
	s_barrier
	s_add_i32 s9, s9, s18
	v_lshl_add_u64 v[208:209], s[4:5], 0, v[162:163]
	s_mov_b32 m0, s9
	ds_read_b128 v[170:173], v201 offset:16384
	ds_read_b128 v[174:177], v201 offset:17408
	ds_read_b128 v[178:181], v201 offset:18432
	ds_read_b128 v[182:185], v201 offset:19456
	ds_read_b128 v[186:189], v201 offset:20480
	ds_read_b128 v[190:193], v201 offset:21504
	ds_read_b128 v[194:197], v201 offset:22528
	ds_read_b128 v[216:219], v201 offset:23552
	global_load_lds_dwordx4 v[208:209], off
	s_add_i32 m0, s9, 0x2000
	s_add_u32 s10, s4, 0x40000
	v_lshl_add_u64 v[220:221], s[4:5], 0, v[164:165]
	s_addc_u32 s11, s5, 0
	s_add_i32 s9, s13, s18
	global_load_lds_dwordx4 v[220:221], off
	v_lshl_add_u64 v[222:223], s[10:11], 0, v[162:163]
	s_mov_b32 m0, s9
	v_lshl_add_u64 v[224:225], s[6:7], 0, v[164:165]
	global_load_lds_dwordx4 v[222:223], off
	v_lshl_add_u64 v[222:223], s[10:11], 0, v[164:165]
	s_add_i32 m0, s9, 0x2000
	s_nop 0
	global_load_lds_dwordx4 v[222:223], off
	v_lshl_add_u64 v[222:223], s[6:7], 0, v[162:163]
	s_mov_b32 m0, s19
	s_nop 0
	global_load_lds_dwordx4 v[222:223], off
	s_mov_b32 m0, s20
	s_nop 0
	global_load_lds_dwordx4 v[224:225], off
	s_waitcnt vmcnt(8)
	s_waitcnt lgkmcnt(0)
	s_barrier
	s_setprio 1
	s_waitcnt lgkmcnt(0)
	v_mfma_f32_16x16x32_bf16 v[62:65], v[130:133], v[170:173], v[62:65]
	v_mfma_f32_16x16x32_bf16 v[58:61], v[138:141], v[170:173], v[58:61]
	v_mfma_f32_16x16x32_bf16 v[46:49], v[130:133], v[178:181], v[46:49]
	v_mfma_f32_16x16x32_bf16 v[42:45], v[138:141], v[178:181], v[42:45]
	v_mfma_f32_16x16x32_bf16 v[30:33], v[130:133], v[186:189], v[30:33]
	v_mfma_f32_16x16x32_bf16 v[26:29], v[138:141], v[186:189], v[26:29]
	v_mfma_f32_16x16x32_bf16 v[14:17], v[130:133], v[194:197], v[14:17]
	v_mfma_f32_16x16x32_bf16 v[10:13], v[138:141], v[194:197], v[10:13]
	v_mfma_f32_16x16x32_bf16 v[62:65], v[134:137], v[174:177], v[62:65]
	v_mfma_f32_16x16x32_bf16 v[58:61], v[142:145], v[174:177], v[58:61]
	v_mfma_f32_16x16x32_bf16 v[46:49], v[134:137], v[182:185], v[46:49]
	v_mfma_f32_16x16x32_bf16 v[42:45], v[142:145], v[182:185], v[42:45]
	v_mfma_f32_16x16x32_bf16 v[30:33], v[134:137], v[190:193], v[30:33]
	v_mfma_f32_16x16x32_bf16 v[26:29], v[142:145], v[190:193], v[26:29]
	v_mfma_f32_16x16x32_bf16 v[14:17], v[134:137], v[216:219], v[14:17]
	v_mfma_f32_16x16x32_bf16 v[10:13], v[142:145], v[216:219], v[10:13]
	s_setprio 0
	s_setprio 1
	v_mfma_f32_16x16x32_bf16 v[54:57], v[146:149], v[170:173], v[54:57]
	v_mfma_f32_16x16x32_bf16 v[50:53], v[154:157], v[170:173], v[50:53]
	v_mfma_f32_16x16x32_bf16 v[38:41], v[146:149], v[178:181], v[38:41]
	v_mfma_f32_16x16x32_bf16 v[34:37], v[154:157], v[178:181], v[34:37]
	v_mfma_f32_16x16x32_bf16 v[22:25], v[146:149], v[186:189], v[22:25]
	v_mfma_f32_16x16x32_bf16 v[18:21], v[154:157], v[186:189], v[18:21]
	v_mfma_f32_16x16x32_bf16 v[6:9], v[146:149], v[194:197], v[6:9]
	v_mfma_f32_16x16x32_bf16 v[2:5], v[154:157], v[194:197], v[2:5]
	v_mfma_f32_16x16x32_bf16 v[54:57], v[150:153], v[174:177], v[54:57]
	v_mfma_f32_16x16x32_bf16 v[50:53], v[158:161], v[174:177], v[50:53]
	v_mfma_f32_16x16x32_bf16 v[38:41], v[150:153], v[182:185], v[38:41]
	v_mfma_f32_16x16x32_bf16 v[34:37], v[158:161], v[182:185], v[34:37]
	v_mfma_f32_16x16x32_bf16 v[22:25], v[150:153], v[190:193], v[22:25]
	v_mfma_f32_16x16x32_bf16 v[18:21], v[158:161], v[190:193], v[18:21]
	v_mfma_f32_16x16x32_bf16 v[6:9], v[150:153], v[216:219], v[6:9]
	v_mfma_f32_16x16x32_bf16 v[2:5], v[158:161], v[216:219], v[2:5]
	s_setprio 0
	s_barrier
	s_add_i32 s9, 0, 0x18000
	s_add_i32 s10, 0, 0x1c000
	v_add_u32_e32 v142, s9, v200
	v_add_u32_e32 v158, s10, v200
	ds_read_b128 v[130:133], v142
	ds_read_b128 v[134:137], v142 offset:1024
	ds_read_b128 v[138:141], v142 offset:2048
	ds_read_b128 v[142:145], v142 offset:3072
	ds_read_b128 v[146:149], v158
	ds_read_b128 v[150:153], v158 offset:1024
	ds_read_b128 v[154:157], v158 offset:2048
	ds_read_b128 v[158:161], v158 offset:3072
	s_add_u32 s6, s6, 0x40000
	s_addc_u32 s7, s7, 0
	s_mov_b32 m0, s21
	v_lshl_add_u64 v[226:227], s[6:7], 0, v[162:163]
	ds_read_b128 v[170:173], v201 offset:32768
	ds_read_b128 v[174:177], v201 offset:33792
	ds_read_b128 v[178:181], v201 offset:34816
	ds_read_b128 v[182:185], v201 offset:35840
	ds_read_b128 v[186:189], v201 offset:36864
	ds_read_b128 v[190:193], v201 offset:37888
	ds_read_b128 v[194:197], v201 offset:38912
	ds_read_b128 v[216:219], v201 offset:39936
	global_load_lds_dwordx4 v[226:227], off
	v_lshl_add_u64 v[226:227], s[6:7], 0, v[164:165]
	s_mov_b32 m0, s22
	s_nop 0
	global_load_lds_dwordx4 v[226:227], off
	s_waitcnt vmcnt(8)
	s_waitcnt lgkmcnt(0)
	s_barrier
	s_setprio 1
	s_waitcnt lgkmcnt(0)
	v_mfma_f32_16x16x32_bf16 v[126:129], v[130:133], v[170:173], v[126:129]
	v_mfma_f32_16x16x32_bf16 v[122:125], v[138:141], v[170:173], v[122:125]
	v_mfma_f32_16x16x32_bf16 v[110:113], v[130:133], v[178:181], v[110:113]
	v_mfma_f32_16x16x32_bf16 v[106:109], v[138:141], v[178:181], v[106:109]
	v_mfma_f32_16x16x32_bf16 v[94:97], v[130:133], v[186:189], v[94:97]
	v_mfma_f32_16x16x32_bf16 v[90:93], v[138:141], v[186:189], v[90:93]
	v_mfma_f32_16x16x32_bf16 v[78:81], v[130:133], v[194:197], v[78:81]
	v_mfma_f32_16x16x32_bf16 v[74:77], v[138:141], v[194:197], v[74:77]
	v_mfma_f32_16x16x32_bf16 v[126:129], v[134:137], v[174:177], v[126:129]
	v_mfma_f32_16x16x32_bf16 v[122:125], v[142:145], v[174:177], v[122:125]
	v_mfma_f32_16x16x32_bf16 v[110:113], v[134:137], v[182:185], v[110:113]
	v_mfma_f32_16x16x32_bf16 v[106:109], v[142:145], v[182:185], v[106:109]
	v_mfma_f32_16x16x32_bf16 v[94:97], v[134:137], v[190:193], v[94:97]
	v_mfma_f32_16x16x32_bf16 v[90:93], v[142:145], v[190:193], v[90:93]
	v_mfma_f32_16x16x32_bf16 v[78:81], v[134:137], v[216:219], v[78:81]
	v_mfma_f32_16x16x32_bf16 v[74:77], v[142:145], v[216:219], v[74:77]
	s_setprio 0
	s_setprio 1
	v_mfma_f32_16x16x32_bf16 v[118:121], v[146:149], v[170:173], v[118:121]
	v_mfma_f32_16x16x32_bf16 v[114:117], v[154:157], v[170:173], v[114:117]
	v_mfma_f32_16x16x32_bf16 v[102:105], v[146:149], v[178:181], v[102:105]
	v_mfma_f32_16x16x32_bf16 v[98:101], v[154:157], v[178:181], v[98:101]
	v_mfma_f32_16x16x32_bf16 v[86:89], v[146:149], v[186:189], v[86:89]
	v_mfma_f32_16x16x32_bf16 v[82:85], v[154:157], v[186:189], v[82:85]
	v_mfma_f32_16x16x32_bf16 v[70:73], v[146:149], v[194:197], v[70:73]
	v_mfma_f32_16x16x32_bf16 v[66:69], v[154:157], v[194:197], v[66:69]
	v_mfma_f32_16x16x32_bf16 v[118:121], v[150:153], v[174:177], v[118:121]
	v_mfma_f32_16x16x32_bf16 v[114:117], v[158:161], v[174:177], v[114:117]
	v_mfma_f32_16x16x32_bf16 v[102:105], v[150:153], v[182:185], v[102:105]
	v_mfma_f32_16x16x32_bf16 v[98:101], v[158:161], v[182:185], v[98:101]
	v_mfma_f32_16x16x32_bf16 v[86:89], v[150:153], v[190:193], v[86:89]
	v_mfma_f32_16x16x32_bf16 v[82:85], v[158:161], v[190:193], v[82:85]
	v_mfma_f32_16x16x32_bf16 v[70:73], v[150:153], v[216:219], v[70:73]
	v_mfma_f32_16x16x32_bf16 v[66:69], v[158:161], v[216:219], v[66:69]
	s_setprio 0
	s_barrier
	s_add_i32 s6, s9, s18
	v_lshl_add_u64 v[208:209], v[208:209], 0, s[96:97]
	s_mov_b32 m0, s6
	ds_read_b128 v[170:173], v201 offset:49152
	ds_read_b128 v[174:177], v201 offset:50176
	ds_read_b128 v[178:181], v201 offset:51200
	ds_read_b128 v[182:185], v201 offset:52224
	ds_read_b128 v[186:189], v201 offset:53248
	ds_read_b128 v[190:193], v201 offset:54272
	ds_read_b128 v[194:197], v201 offset:55296
	ds_read_b128 v[216:219], v201 offset:56320
	global_load_lds_dwordx4 v[208:209], off
	s_add_i32 m0, s6, 0x2000
	s_add_u32 s4, s4, 0x40080
	v_lshl_add_u64 v[208:209], v[220:221], 0, s[96:97]
	s_addc_u32 s5, s5, 0
	s_add_i32 s6, s10, s18
	global_load_lds_dwordx4 v[208:209], off
	v_lshl_add_u64 v[208:209], s[4:5], 0, v[162:163]
	s_mov_b32 m0, s6
	s_nop 0
	global_load_lds_dwordx4 v[208:209], off
	v_lshl_add_u64 v[208:209], s[4:5], 0, v[164:165]
	s_add_i32 m0, s6, 0x2000
	s_nop 0
	global_load_lds_dwordx4 v[208:209], off
	v_lshl_add_u64 v[208:209], v[222:223], 0, s[96:97]
	s_mov_b32 m0, s64
	s_nop 0
	global_load_lds_dwordx4 v[208:209], off
	v_lshl_add_u64 v[208:209], v[224:225], 0, s[96:97]
	s_mov_b32 m0, s65
	s_nop 0
	global_load_lds_dwordx4 v[208:209], off
	s_waitcnt vmcnt(8)
	s_waitcnt lgkmcnt(0)
	s_barrier
	s_setprio 1
	s_waitcnt lgkmcnt(0)
	v_mfma_f32_16x16x32_bf16 v[62:65], v[130:133], v[170:173], v[62:65]
	v_mfma_f32_16x16x32_bf16 v[58:61], v[138:141], v[170:173], v[58:61]
	v_mfma_f32_16x16x32_bf16 v[46:49], v[130:133], v[178:181], v[46:49]
	v_mfma_f32_16x16x32_bf16 v[42:45], v[138:141], v[178:181], v[42:45]
	v_mfma_f32_16x16x32_bf16 v[30:33], v[130:133], v[186:189], v[30:33]
	v_mfma_f32_16x16x32_bf16 v[26:29], v[138:141], v[186:189], v[26:29]
	v_mfma_f32_16x16x32_bf16 v[14:17], v[130:133], v[194:197], v[14:17]
	v_mfma_f32_16x16x32_bf16 v[10:13], v[138:141], v[194:197], v[10:13]
	v_mfma_f32_16x16x32_bf16 v[62:65], v[134:137], v[174:177], v[62:65]
	v_mfma_f32_16x16x32_bf16 v[58:61], v[142:145], v[174:177], v[58:61]
	v_mfma_f32_16x16x32_bf16 v[46:49], v[134:137], v[182:185], v[46:49]
	v_mfma_f32_16x16x32_bf16 v[42:45], v[142:145], v[182:185], v[42:45]
	v_mfma_f32_16x16x32_bf16 v[30:33], v[134:137], v[190:193], v[30:33]
	v_mfma_f32_16x16x32_bf16 v[26:29], v[142:145], v[190:193], v[26:29]
	v_mfma_f32_16x16x32_bf16 v[14:17], v[134:137], v[216:219], v[14:17]
	v_mfma_f32_16x16x32_bf16 v[10:13], v[142:145], v[216:219], v[10:13]
	s_setprio 0
	s_setprio 1
	v_mfma_f32_16x16x32_bf16 v[54:57], v[146:149], v[170:173], v[54:57]
	v_mfma_f32_16x16x32_bf16 v[50:53], v[154:157], v[170:173], v[50:53]
	v_mfma_f32_16x16x32_bf16 v[38:41], v[146:149], v[178:181], v[38:41]
	v_mfma_f32_16x16x32_bf16 v[34:37], v[154:157], v[178:181], v[34:37]
	v_mfma_f32_16x16x32_bf16 v[22:25], v[146:149], v[186:189], v[22:25]
	v_mfma_f32_16x16x32_bf16 v[18:21], v[154:157], v[186:189], v[18:21]
	v_mfma_f32_16x16x32_bf16 v[6:9], v[146:149], v[194:197], v[6:9]
	v_mfma_f32_16x16x32_bf16 v[2:5], v[154:157], v[194:197], v[2:5]
	v_mfma_f32_16x16x32_bf16 v[54:57], v[150:153], v[174:177], v[54:57]
	v_mfma_f32_16x16x32_bf16 v[50:53], v[158:161], v[174:177], v[50:53]
	v_mfma_f32_16x16x32_bf16 v[38:41], v[150:153], v[182:185], v[38:41]
	v_mfma_f32_16x16x32_bf16 v[34:37], v[158:161], v[182:185], v[34:37]
	v_mfma_f32_16x16x32_bf16 v[22:25], v[150:153], v[190:193], v[22:25]
	v_mfma_f32_16x16x32_bf16 v[18:21], v[158:161], v[190:193], v[18:21]
	v_mfma_f32_16x16x32_bf16 v[6:9], v[150:153], v[216:219], v[6:9]
	v_mfma_f32_16x16x32_bf16 v[2:5], v[158:161], v[216:219], v[2:5]
	s_setprio 0
	s_barrier
	s_add_i32 s8, s8, 2
	s_add_u32 s0, s0, 0x100
	s_addc_u32 s1, s1, 0
	s_add_u32 s2, s2, 0x100
	s_addc_u32 s3, s3, 0
	s_cmp_gt_u32 s8, 13
	s_cbranch_scc0 .LBB0_147
	s_and_b64 vcc, exec, s[50:51]
	s_cbranch_vccz .LBB0_150
	s_barrier

.LBB0_826:
	s_add_u32 s4, s4, 0x40080
	s_addc_u32 s5, s5, 0
	s_add_u32 s33, s6, 0x100
	s_addc_u32 s55, s7, 0
	s_mov_b32 s56, -2
.LBB0_827:
	s_add_u32 s6, s4, 0xfffc0080
	s_addc_u32 s7, s5, -1
	s_add_i32 s57, 0, 0x10000
	s_cmp_eq_u32 s56, 12
	s_cselect_b32 s9, s49, s7
	s_cselect_b32 s8, s48, s6
	s_cselect_b32 s7, s51, s55
	s_cselect_b32 s6, s50, s33
	s_add_i32 s60, 0, 0x14000
	v_add_u32_e32 v78, s57, v164
	v_add_u32_e32 v160, s60, v164
	ds_read_b128 v[66:69], v78
	ds_read_b128 v[70:73], v78 offset:1024
	ds_read_b128 v[74:77], v78 offset:2048
	ds_read_b128 v[78:81], v78 offset:3072
	ds_read_b128 v[156:159], v160
	ds_read_b128 v[166:169], v160 offset:1024
	ds_read_b128 v[170:173], v160 offset:2048
	ds_read_b128 v[174:177], v160 offset:3072
	v_lshl_add_u64 v[160:161], s[4:5], 0, v[152:153]
	s_add_i32 m0, s13, 0xc000
	ds_read_b128 v[178:181], v165
	ds_read_b128 v[182:185], v165 offset:1024
	ds_read_b128 v[186:189], v165 offset:2048
	ds_read_b128 v[190:193], v165 offset:3072
	ds_read_b128 v[194:197], v165 offset:4096
	ds_read_b128 v[198:201], v165 offset:5120
	ds_read_b128 v[216:219], v165 offset:6144
	ds_read_b128 v[220:223], v165 offset:7168
	global_load_lds_dwordx4 v[160:161], off
	v_lshl_add_u64 v[160:161], s[4:5], 0, v[154:155]
	s_add_i32 m0, s13, 0xe000
	s_nop 0
	global_load_lds_dwordx4 v[160:161], off
	s_cmp_lg_u32 s56, -2
	s_cbranch_scc1 .Lzf5_skip
	v_mov_b64_e32 v[2:3], 0
	v_mov_b64_e32 v[4:5], 0
	v_mov_b64_e32 v[6:7], 0
	v_mov_b64_e32 v[8:9], 0
	v_mov_b64_e32 v[10:11], 0
	v_mov_b64_e32 v[12:13], 0
	v_mov_b64_e32 v[14:15], 0
	v_mov_b64_e32 v[16:17], 0
	v_mov_b64_e32 v[18:19], 0
	v_mov_b64_e32 v[20:21], 0
	v_mov_b64_e32 v[22:23], 0
	v_mov_b64_e32 v[24:25], 0
	v_mov_b64_e32 v[26:27], 0
	v_mov_b64_e32 v[28:29], 0
	v_mov_b64_e32 v[30:31], 0
	v_mov_b64_e32 v[32:33], 0
	v_mov_b64_e32 v[34:35], 0
	v_mov_b64_e32 v[36:37], 0
	v_mov_b64_e32 v[38:39], 0
	v_mov_b64_e32 v[40:41], 0
	v_mov_b64_e32 v[42:43], 0
	v_mov_b64_e32 v[44:45], 0
	v_mov_b64_e32 v[46:47], 0
	v_mov_b64_e32 v[48:49], 0
	v_mov_b64_e32 v[50:51], 0
	v_mov_b64_e32 v[52:53], 0
	v_mov_b64_e32 v[54:55], 0
	v_mov_b64_e32 v[56:57], 0
	v_mov_b64_e32 v[58:59], 0
	v_mov_b64_e32 v[60:61], 0
	v_mov_b64_e32 v[62:63], 0
	v_mov_b64_e32 v[64:65], 0
	v_mov_b64_e32 v[82:83], 0
	v_mov_b64_e32 v[84:85], 0
	v_mov_b64_e32 v[86:87], 0
	v_mov_b64_e32 v[88:89], 0
	v_mov_b64_e32 v[90:91], 0
	v_mov_b64_e32 v[92:93], 0
	v_mov_b64_e32 v[94:95], 0
	v_mov_b64_e32 v[96:97], 0
	v_mov_b64_e32 v[98:99], 0
	v_mov_b64_e32 v[100:101], 0
	v_mov_b64_e32 v[102:103], 0
	v_mov_b64_e32 v[104:105], 0
	v_mov_b64_e32 v[106:107], 0
	v_mov_b64_e32 v[108:109], 0
	v_mov_b64_e32 v[110:111], 0
	v_mov_b64_e32 v[112:113], 0
	v_mov_b64_e32 v[114:115], 0
	v_mov_b64_e32 v[116:117], 0
	v_mov_b64_e32 v[118:119], 0
	v_mov_b64_e32 v[120:121], 0
	v_mov_b64_e32 v[122:123], 0
	v_mov_b64_e32 v[124:125], 0
	v_mov_b64_e32 v[126:127], 0
	v_mov_b64_e32 v[128:129], 0
	v_mov_b64_e32 v[130:131], 0
	v_mov_b64_e32 v[132:133], 0
	v_mov_b64_e32 v[134:135], 0
	v_mov_b64_e32 v[136:137], 0
	v_mov_b64_e32 v[138:139], 0
	v_mov_b64_e32 v[140:141], 0
	v_mov_b64_e32 v[142:143], 0
	v_mov_b64_e32 v[144:145], 0
.Lzf5_skip:
	s_waitcnt vmcnt(8)
	s_waitcnt lgkmcnt(0)
	s_barrier
	s_setprio 1
	s_waitcnt lgkmcnt(0)
	v_mfma_f32_16x16x32_bf16 v[142:145], v[66:69], v[178:181], v[142:145]
	v_mfma_f32_16x16x32_bf16 v[138:141], v[74:77], v[178:181], v[138:141]
	v_mfma_f32_16x16x32_bf16 v[126:129], v[66:69], v[186:189], v[126:129]
	v_mfma_f32_16x16x32_bf16 v[122:125], v[74:77], v[186:189], v[122:125]
	v_mfma_f32_16x16x32_bf16 v[110:113], v[66:69], v[194:197], v[110:113]
	v_mfma_f32_16x16x32_bf16 v[106:109], v[74:77], v[194:197], v[106:109]
	v_mfma_f32_16x16x32_bf16 v[94:97], v[66:69], v[216:219], v[94:97]
	v_mfma_f32_16x16x32_bf16 v[90:93], v[74:77], v[216:219], v[90:93]
	v_mfma_f32_16x16x32_bf16 v[142:145], v[70:73], v[182:185], v[142:145]
	v_mfma_f32_16x16x32_bf16 v[138:141], v[78:81], v[182:185], v[138:141]
	v_mfma_f32_16x16x32_bf16 v[126:129], v[70:73], v[190:193], v[126:129]
	v_mfma_f32_16x16x32_bf16 v[122:125], v[78:81], v[190:193], v[122:125]
	v_mfma_f32_16x16x32_bf16 v[110:113], v[70:73], v[198:201], v[110:113]
	v_mfma_f32_16x16x32_bf16 v[106:109], v[78:81], v[198:201], v[106:109]
	v_mfma_f32_16x16x32_bf16 v[94:97], v[70:73], v[220:223], v[94:97]
	v_mfma_f32_16x16x32_bf16 v[90:93], v[78:81], v[220:223], v[90:93]
	s_setprio 0
	s_setprio 1
	v_mfma_f32_16x16x32_bf16 v[134:137], v[156:159], v[178:181], v[134:137]
	v_mfma_f32_16x16x32_bf16 v[130:133], v[170:173], v[178:181], v[130:133]
	v_mfma_f32_16x16x32_bf16 v[118:121], v[156:159], v[186:189], v[118:121]
	v_mfma_f32_16x16x32_bf16 v[114:117], v[170:173], v[186:189], v[114:117]
	v_mfma_f32_16x16x32_bf16 v[102:105], v[156:159], v[194:197], v[102:105]
	v_mfma_f32_16x16x32_bf16 v[98:101], v[170:173], v[194:197], v[98:101]
	v_mfma_f32_16x16x32_bf16 v[86:89], v[156:159], v[216:219], v[86:89]
	v_mfma_f32_16x16x32_bf16 v[82:85], v[170:173], v[216:219], v[82:85]
	v_mfma_f32_16x16x32_bf16 v[134:137], v[166:169], v[182:185], v[134:137]
	v_mfma_f32_16x16x32_bf16 v[130:133], v[174:177], v[182:185], v[130:133]
	v_mfma_f32_16x16x32_bf16 v[118:121], v[166:169], v[190:193], v[118:121]
	v_mfma_f32_16x16x32_bf16 v[114:117], v[174:177], v[190:193], v[114:117]
	v_mfma_f32_16x16x32_bf16 v[102:105], v[166:169], v[198:201], v[102:105]
	v_mfma_f32_16x16x32_bf16 v[98:101], v[174:177], v[198:201], v[98:101]
	v_mfma_f32_16x16x32_bf16 v[86:89], v[166:169], v[220:223], v[86:89]
	v_mfma_f32_16x16x32_bf16 v[82:85], v[174:177], v[220:223], v[82:85]
	s_setprio 0
	s_barrier
	s_add_i32 s57, s57, s21
	v_lshl_add_u64 v[160:161], s[6:7], 0, v[0:1]
	s_mov_b32 m0, s57
	ds_read_b128 v[178:181], v165 offset:16384
	ds_read_b128 v[182:185], v165 offset:17408
	ds_read_b128 v[186:189], v165 offset:18432
	ds_read_b128 v[190:193], v165 offset:19456
	ds_read_b128 v[194:197], v165 offset:20480
	ds_read_b128 v[198:201], v165 offset:21504
	ds_read_b128 v[216:219], v165 offset:22528
	ds_read_b128 v[220:223], v165 offset:23552
	global_load_lds_dwordx4 v[160:161], off
	s_add_i32 m0, s57, 0x2000
	s_add_u32 s58, s6, 0x40000
	v_lshl_add_u64 v[208:209], s[6:7], 0, v[150:151]
	s_addc_u32 s59, s7, 0
	s_add_i32 s57, s60, s21
	global_load_lds_dwordx4 v[208:209], off
	v_lshl_add_u64 v[224:225], s[58:59], 0, v[0:1]
	s_mov_b32 m0, s57
	v_lshl_add_u64 v[226:227], s[8:9], 0, v[148:149]
	global_load_lds_dwordx4 v[224:225], off
	v_lshl_add_u64 v[224:225], s[58:59], 0, v[150:151]
	s_add_i32 m0, s57, 0x2000
	s_nop 0
	global_load_lds_dwordx4 v[224:225], off
	v_lshl_add_u64 v[224:225], s[8:9], 0, v[146:147]
	s_mov_b32 m0, s13
	s_nop 0
	global_load_lds_dwordx4 v[224:225], off
	s_mov_b32 m0, s22
	s_nop 0
	global_load_lds_dwordx4 v[226:227], off
	s_waitcnt vmcnt(8)
	s_waitcnt lgkmcnt(0)
	s_barrier
	s_setprio 1
	s_waitcnt lgkmcnt(0)
	v_mfma_f32_16x16x32_bf16 v[62:65], v[66:69], v[178:181], v[62:65]
	v_mfma_f32_16x16x32_bf16 v[58:61], v[74:77], v[178:181], v[58:61]
	v_mfma_f32_16x16x32_bf16 v[46:49], v[66:69], v[186:189], v[46:49]
	v_mfma_f32_16x16x32_bf16 v[42:45], v[74:77], v[186:189], v[42:45]
	v_mfma_f32_16x16x32_bf16 v[30:33], v[66:69], v[194:197], v[30:33]
	v_mfma_f32_16x16x32_bf16 v[26:29], v[74:77], v[194:197], v[26:29]
	v_mfma_f32_16x16x32_bf16 v[14:17], v[66:69], v[216:219], v[14:17]
	v_mfma_f32_16x16x32_bf16 v[10:13], v[74:77], v[216:219], v[10:13]
	v_mfma_f32_16x16x32_bf16 v[62:65], v[70:73], v[182:185], v[62:65]
	v_mfma_f32_16x16x32_bf16 v[58:61], v[78:81], v[182:185], v[58:61]
	v_mfma_f32_16x16x32_bf16 v[46:49], v[70:73], v[190:193], v[46:49]
	v_mfma_f32_16x16x32_bf16 v[42:45], v[78:81], v[190:193], v[42:45]
	v_mfma_f32_16x16x32_bf16 v[30:33], v[70:73], v[198:201], v[30:33]
	v_mfma_f32_16x16x32_bf16 v[26:29], v[78:81], v[198:201], v[26:29]
	v_mfma_f32_16x16x32_bf16 v[14:17], v[70:73], v[220:223], v[14:17]
	v_mfma_f32_16x16x32_bf16 v[10:13], v[78:81], v[220:223], v[10:13]
	s_setprio 0
	s_setprio 1
	v_mfma_f32_16x16x32_bf16 v[54:57], v[156:159], v[178:181], v[54:57]
	v_mfma_f32_16x16x32_bf16 v[50:53], v[170:173], v[178:181], v[50:53]
	v_mfma_f32_16x16x32_bf16 v[38:41], v[156:159], v[186:189], v[38:41]
	v_mfma_f32_16x16x32_bf16 v[34:37], v[170:173], v[186:189], v[34:37]
	v_mfma_f32_16x16x32_bf16 v[22:25], v[156:159], v[194:197], v[22:25]
	v_mfma_f32_16x16x32_bf16 v[18:21], v[170:173], v[194:197], v[18:21]
	v_mfma_f32_16x16x32_bf16 v[6:9], v[156:159], v[216:219], v[6:9]
	v_mfma_f32_16x16x32_bf16 v[2:5], v[170:173], v[216:219], v[2:5]
	v_mfma_f32_16x16x32_bf16 v[54:57], v[166:169], v[182:185], v[54:57]
	v_mfma_f32_16x16x32_bf16 v[50:53], v[174:177], v[182:185], v[50:53]
	v_mfma_f32_16x16x32_bf16 v[38:41], v[166:169], v[190:193], v[38:41]
	v_mfma_f32_16x16x32_bf16 v[34:37], v[174:177], v[190:193], v[34:37]
	v_mfma_f32_16x16x32_bf16 v[22:25], v[166:169], v[198:201], v[22:25]
	v_mfma_f32_16x16x32_bf16 v[18:21], v[174:177], v[198:201], v[18:21]
	v_mfma_f32_16x16x32_bf16 v[6:9], v[166:169], v[220:223], v[6:9]
	v_mfma_f32_16x16x32_bf16 v[2:5], v[174:177], v[220:223], v[2:5]
	s_setprio 0
	s_barrier
	s_add_i32 s57, 0, 0x18000
	s_add_i32 s58, 0, 0x1c000
	v_add_u32_e32 v78, s57, v164
	v_add_u32_e32 v174, s58, v164
	ds_read_b128 v[66:69], v78
	ds_read_b128 v[70:73], v78 offset:1024
	ds_read_b128 v[74:77], v78 offset:2048
	ds_read_b128 v[78:81], v78 offset:3072
	ds_read_b128 v[156:159], v174
	ds_read_b128 v[166:169], v174 offset:1024
	ds_read_b128 v[170:173], v174 offset:2048
	ds_read_b128 v[174:177], v174 offset:3072
	s_add_u32 s8, s8, 0x40000
	s_addc_u32 s9, s9, 0
	s_mov_b32 m0, s23
	v_lshl_add_u64 v[228:229], s[8:9], 0, v[146:147]
	ds_read_b128 v[178:181], v165 offset:32768
	ds_read_b128 v[182:185], v165 offset:33792
	ds_read_b128 v[186:189], v165 offset:34816
	ds_read_b128 v[190:193], v165 offset:35840
	ds_read_b128 v[194:197], v165 offset:36864
	ds_read_b128 v[198:201], v165 offset:37888
	ds_read_b128 v[216:219], v165 offset:38912
	ds_read_b128 v[220:223], v165 offset:39936
	global_load_lds_dwordx4 v[228:229], off
	v_lshl_add_u64 v[228:229], s[8:9], 0, v[148:149]
	s_mov_b32 m0, s24
	s_nop 0
	global_load_lds_dwordx4 v[228:229], off
	s_waitcnt vmcnt(8)
	s_waitcnt lgkmcnt(0)
	s_barrier
	s_setprio 1
	s_waitcnt lgkmcnt(0)
	v_mfma_f32_16x16x32_bf16 v[142:145], v[66:69], v[178:181], v[142:145]
	v_mfma_f32_16x16x32_bf16 v[138:141], v[74:77], v[178:181], v[138:141]
	v_mfma_f32_16x16x32_bf16 v[126:129], v[66:69], v[186:189], v[126:129]
	v_mfma_f32_16x16x32_bf16 v[122:125], v[74:77], v[186:189], v[122:125]
	v_mfma_f32_16x16x32_bf16 v[110:113], v[66:69], v[194:197], v[110:113]
	v_mfma_f32_16x16x32_bf16 v[106:109], v[74:77], v[194:197], v[106:109]
	v_mfma_f32_16x16x32_bf16 v[94:97], v[66:69], v[216:219], v[94:97]
	v_mfma_f32_16x16x32_bf16 v[90:93], v[74:77], v[216:219], v[90:93]
	v_mfma_f32_16x16x32_bf16 v[142:145], v[70:73], v[182:185], v[142:145]
	v_mfma_f32_16x16x32_bf16 v[138:141], v[78:81], v[182:185], v[138:141]
	v_mfma_f32_16x16x32_bf16 v[126:129], v[70:73], v[190:193], v[126:129]
	v_mfma_f32_16x16x32_bf16 v[122:125], v[78:81], v[190:193], v[122:125]
	v_mfma_f32_16x16x32_bf16 v[110:113], v[70:73], v[198:201], v[110:113]
	v_mfma_f32_16x16x32_bf16 v[106:109], v[78:81], v[198:201], v[106:109]
	v_mfma_f32_16x16x32_bf16 v[94:97], v[70:73], v[220:223], v[94:97]
	v_mfma_f32_16x16x32_bf16 v[90:93], v[78:81], v[220:223], v[90:93]
	s_setprio 0
	s_setprio 1
	v_mfma_f32_16x16x32_bf16 v[134:137], v[156:159], v[178:181], v[134:137]
	v_mfma_f32_16x16x32_bf16 v[130:133], v[170:173], v[178:181], v[130:133]
	v_mfma_f32_16x16x32_bf16 v[118:121], v[156:159], v[186:189], v[118:121]
	v_mfma_f32_16x16x32_bf16 v[114:117], v[170:173], v[186:189], v[114:117]
	v_mfma_f32_16x16x32_bf16 v[102:105], v[156:159], v[194:197], v[102:105]
	v_mfma_f32_16x16x32_bf16 v[98:101], v[170:173], v[194:197], v[98:101]
	v_mfma_f32_16x16x32_bf16 v[86:89], v[156:159], v[216:219], v[86:89]
	v_mfma_f32_16x16x32_bf16 v[82:85], v[170:173], v[216:219], v[82:85]
	v_mfma_f32_16x16x32_bf16 v[134:137], v[166:169], v[182:185], v[134:137]
	v_mfma_f32_16x16x32_bf16 v[130:133], v[174:177], v[182:185], v[130:133]
	v_mfma_f32_16x16x32_bf16 v[118:121], v[166:169], v[190:193], v[118:121]
	v_mfma_f32_16x16x32_bf16 v[114:117], v[174:177], v[190:193], v[114:117]
	v_mfma_f32_16x16x32_bf16 v[102:105], v[166:169], v[198:201], v[102:105]
	v_mfma_f32_16x16x32_bf16 v[98:101], v[174:177], v[198:201], v[98:101]
	v_mfma_f32_16x16x32_bf16 v[86:89], v[166:169], v[220:223], v[86:89]
	v_mfma_f32_16x16x32_bf16 v[82:85], v[174:177], v[220:223], v[82:85]
	s_setprio 0
	s_barrier
	s_add_i32 s8, s57, s21
	v_lshl_add_u64 v[160:161], v[160:161], 0, s[96:97]
	s_mov_b32 m0, s8
	ds_read_b128 v[178:181], v165 offset:49152
	ds_read_b128 v[182:185], v165 offset:50176
	ds_read_b128 v[186:189], v165 offset:51200
	ds_read_b128 v[190:193], v165 offset:52224
	ds_read_b128 v[194:197], v165 offset:53248
	ds_read_b128 v[198:201], v165 offset:54272
	ds_read_b128 v[216:219], v165 offset:55296
	ds_read_b128 v[220:223], v165 offset:56320
	global_load_lds_dwordx4 v[160:161], off
	s_add_i32 m0, s8, 0x2000
	s_add_u32 s6, s6, 0x40080
	v_lshl_add_u64 v[160:161], v[208:209], 0, s[96:97]
	s_addc_u32 s7, s7, 0
	s_add_i32 s8, s58, s21
	global_load_lds_dwordx4 v[160:161], off
	v_lshl_add_u64 v[160:161], s[6:7], 0, v[0:1]
	s_mov_b32 m0, s8
	s_nop 0
	global_load_lds_dwordx4 v[160:161], off
	v_lshl_add_u64 v[160:161], s[6:7], 0, v[150:151]
	s_add_i32 m0, s8, 0x2000
	s_nop 0
	global_load_lds_dwordx4 v[160:161], off
	v_lshl_add_u64 v[160:161], v[224:225], 0, s[96:97]
	s_mov_b32 m0, s27
	s_nop 0
	global_load_lds_dwordx4 v[160:161], off
	v_lshl_add_u64 v[160:161], v[226:227], 0, s[96:97]
	s_mov_b32 m0, s28
	s_nop 0
	global_load_lds_dwordx4 v[160:161], off
	s_waitcnt vmcnt(8)
	s_waitcnt lgkmcnt(0)
	s_barrier
	s_setprio 1
	s_waitcnt lgkmcnt(0)
	v_mfma_f32_16x16x32_bf16 v[62:65], v[66:69], v[178:181], v[62:65]
	v_mfma_f32_16x16x32_bf16 v[58:61], v[74:77], v[178:181], v[58:61]
	v_mfma_f32_16x16x32_bf16 v[46:49], v[66:69], v[186:189], v[46:49]
	v_mfma_f32_16x16x32_bf16 v[42:45], v[74:77], v[186:189], v[42:45]
	v_mfma_f32_16x16x32_bf16 v[30:33], v[66:69], v[194:197], v[30:33]
	v_mfma_f32_16x16x32_bf16 v[26:29], v[74:77], v[194:197], v[26:29]
	v_mfma_f32_16x16x32_bf16 v[14:17], v[66:69], v[216:219], v[14:17]
	v_mfma_f32_16x16x32_bf16 v[10:13], v[74:77], v[216:219], v[10:13]
	v_mfma_f32_16x16x32_bf16 v[62:65], v[70:73], v[182:185], v[62:65]
	v_mfma_f32_16x16x32_bf16 v[58:61], v[78:81], v[182:185], v[58:61]
	v_mfma_f32_16x16x32_bf16 v[46:49], v[70:73], v[190:193], v[46:49]
	v_mfma_f32_16x16x32_bf16 v[42:45], v[78:81], v[190:193], v[42:45]
	v_mfma_f32_16x16x32_bf16 v[30:33], v[70:73], v[198:201], v[30:33]
	v_mfma_f32_16x16x32_bf16 v[26:29], v[78:81], v[198:201], v[26:29]
	v_mfma_f32_16x16x32_bf16 v[14:17], v[70:73], v[220:223], v[14:17]
	v_mfma_f32_16x16x32_bf16 v[10:13], v[78:81], v[220:223], v[10:13]
	s_setprio 0
	s_setprio 1
	v_mfma_f32_16x16x32_bf16 v[54:57], v[156:159], v[178:181], v[54:57]
	v_mfma_f32_16x16x32_bf16 v[50:53], v[170:173], v[178:181], v[50:53]
	v_mfma_f32_16x16x32_bf16 v[38:41], v[156:159], v[186:189], v[38:41]
	v_mfma_f32_16x16x32_bf16 v[34:37], v[170:173], v[186:189], v[34:37]
	v_mfma_f32_16x16x32_bf16 v[22:25], v[156:159], v[194:197], v[22:25]
	v_mfma_f32_16x16x32_bf16 v[18:21], v[170:173], v[194:197], v[18:21]
	v_mfma_f32_16x16x32_bf16 v[6:9], v[156:159], v[216:219], v[6:9]
	v_mfma_f32_16x16x32_bf16 v[2:5], v[170:173], v[216:219], v[2:5]
	v_mfma_f32_16x16x32_bf16 v[54:57], v[166:169], v[182:185], v[54:57]
	v_mfma_f32_16x16x32_bf16 v[50:53], v[174:177], v[182:185], v[50:53]
	v_mfma_f32_16x16x32_bf16 v[38:41], v[166:169], v[190:193], v[38:41]
	v_mfma_f32_16x16x32_bf16 v[34:37], v[174:177], v[190:193], v[34:37]
	v_mfma_f32_16x16x32_bf16 v[22:25], v[166:169], v[198:201], v[22:25]
	v_mfma_f32_16x16x32_bf16 v[18:21], v[174:177], v[198:201], v[18:21]
	v_mfma_f32_16x16x32_bf16 v[6:9], v[166:169], v[220:223], v[6:9]
	v_mfma_f32_16x16x32_bf16 v[2:5], v[174:177], v[220:223], v[2:5]
	s_setprio 0
	s_barrier
	s_add_i32 s56, s56, 2
	s_add_u32 s4, s4, 0x100
	s_addc_u32 s5, s5, 0
	s_add_u32 s33, s33, 0x100
	s_addc_u32 s55, s55, 0
	s_cmp_gt_u32 s56, 13
	s_cbranch_scc0 .LBB0_827
	s_and_b64 vcc, exec, s[44:45]
	s_cbranch_vccz .LBB0_830
	s_barrier
